# v36 + SWA in-loop tiles get the same half-stagger (waves 0-3 rendezvous after QK reads, waves 4-7 at tile end)
# speedup vs baseline: 1.0004x; 1.0004x over previous
; #define LAS __attribute__((address_space(3)))
; #define ATT_STORE(S, buf) do { LAS unsigned char* sb_ = lds + (buf) * BUFB; \
;         *(LAS u32x4*)(sb_ + kwoff) = kreg##S; \
;         if (TY == 2 && tid < 256) *(LAS u32x4*)(sb_ + kwoff2) = kreg2##S; \
;         *(LAS u32x4*)(sb_ + KBYTES + (ki * VSTR + kc * 8) * 2) = vreg##S; \
;         if (TY == 1 && tid < 64) *(LAS float*)(sb_ + KBYTES + VBYTES + tid * 4) = freg##S; } while (0)
; template <int TY> __device__ __forceinline__ void attn_unit(LAS unsigned char* lds, const AttnArgs& a, int b, int h, int qt, int wave_s) {
;     ...
;         { const int Jn = J + 2 <= J1 ? J + 2 : J1; if (hf == 0) ATT_LOAD(A, Jn); else ATT_LOAD(B, Jn); }
;         const bool skip = (64 * J > ewhi) || (TY == 0 && 64 * J + 63 + 127 < ewlo);
;         if (!skip) {
;         int lim[2]; f32x4 cinit[2];
; #pragma unroll
;         for (int qb = 0; qb < 2; ++qb) {
;             lim[qb] = eq[qb] - 64 * J - 4 * fq;
;             const float c0 = TY == 0 ? -(mrun[qb] + slope2 * (float)lim[qb]) : -mrun[qb];
;             cinit[qb] = (f32x4){c0, c0, c0, c0};
;         }
;         f32x4 s[2][4];
;         bf16x8 kfr[4][NDS];
; #pragma unroll
;         for (int kb = 0; kb < 4; ++kb)
; #pragma unroll
;             for (int ds = 0; ds < NDS; ++ds) kfr[kb][ds] = *(const LAS bf16x8*)(sb + koff + (kb * NDS + ds) * 1024);
; #pragma unroll
;         for (int kb = 0; kb < 4; ++kb) {
; #pragma unroll
;             for (int ds = 0; ds < NDS; ++ds) {
;                 s[0][kb] = __builtin_amdgcn_mfma_f32_16x16x32_bf16(kfr[kb][ds], qf[0][ds], ds == 0 ? cinit[0] : s[0][kb], 0, 0, 0);
;                 s[1][kb] = __builtin_amdgcn_mfma_f32_16x16x32_bf16(kfr[kb][ds], qf[1][ds], ds == 0 ? cinit[1] : s[1][kb], 0, 0, 0);
;             }
;         }
;         bf16x8 vf[4][2];
; #pragma unroll
;         for (int db = 0; db < 4; ++db)
; #pragma unroll
;             for (int G = 0; G < 2; ++G) {
;                 LAS unsigned char* vp = sb + voff + (32 * G * VSTR + 16 * db) * 2;
;                 const v4i16_t lo = __builtin_amdgcn_ds_read_tr16_b64_v4i16((LAS v4i16_t*)vp), hi = __builtin_amdgcn_ds_read_tr16_b64_v4i16((LAS v4i16_t*)(vp + 16 * VSTR * 2));
;                 vf[db][G] = (bf16x8){lo[0], lo[1], lo[2], lo[3], hi[0], hi[1], hi[2], hi[3]};
;             }
;     ...
;         if (J < J1) { if (hf == 0) ATT_STORE(B, 1); else ATT_STORE(A, 0); }
;         __syncthreads();
.LBB0_798:
	s_add_i32 s66, s53, -1
	s_min_i32 s4, s66, s45
	v_lshl_add_u32 v1, s4, 6, v155
	v_max_i32_e32 v20, 48, v1
	v_add_u32_e32 v18, s42, v1
	v_add_u32_e32 v20, s47, v20
	v_cmp_lt_i32_e32 vcc, 63, v1
	s_cmp_gt_i32 s48, s46
	s_nop 0
	v_cndmask_b32_e32 v1, v20, v18, vcc
	v_mad_i64_i32 v[20:21], s[4:5], v1, s40, v[160:161]
	s_waitcnt vmcnt(0)
	v_mad_i64_i32 v[78:79], s[4:5], v1, s40, v[162:163]
	global_load_dwordx4 v[74:77], v[20:21], off
	s_nop 0
	global_load_dwordx4 v[78:81], v[78:79], off
	s_cselect_b64 s[4:5], -1, 0
	s_add_i32 s6, s48, 0xbe
	s_cmp_lt_i32 s6, s52
	s_cselect_b64 s[6:7], -1, 0
	s_or_b64 s[4:5], s[4:5], s[6:7]
	s_andn2_b64 vcc, exec, s[4:5]
	s_cbranch_vccz .LBB0_805
	v_add_u32_e32 v195, 0x41, v194
	v_cvt_f32_i32_e32 v18, v195
	v_add_u32_e32 v1, 0, v193
	ds_read_b128 v[82:85], v1
	ds_read_b128 v[86:89], v1 offset:1024
	ds_read_b128 v[98:101], v1 offset:2048
	ds_read_b128 v[102:105], v1 offset:3072
	ds_read_b128 v[118:121], v1 offset:4096
	ds_read_b128 v[134:137], v1 offset:5120
	v_add_u32_e32 v196, 0x51, v194
	v_fma_f32 v18, v157, v18, v159
	ds_read_b128 v[208:211], v1 offset:6144
	ds_read_b128 v[212:215], v1 offset:7168
	v_cvt_f32_i32_e32 v1, v196
	v_xor_b32_e32 v90, 0x80000000, v18
	v_mov_b32_e32 v91, v90
	v_mov_b32_e32 v92, v90
	v_mov_b32_e32 v93, v90
	v_fma_f32 v1, v157, v1, v158
	v_xor_b32_e32 v216, 0x80000000, v1
	s_waitcnt lgkmcnt(7)
	v_mfma_f32_16x16x32_bf16 v[94:97], v[82:85], v[14:17], v[90:93]
	v_mov_b32_e32 v217, v216
	v_mov_b32_e32 v218, v216
	v_mov_b32_e32 v219, v216
	s_waitcnt lgkmcnt(6)
	v_mfma_f32_16x16x32_bf16 v[130:133], v[86:89], v[38:41], v[94:97]
	v_add_u32_e32 v1, 0, v192
	v_add_u32_e32 v20, 63, v194
	v_add_u32_e32 v18, 0x50, v194
	s_waitcnt lgkmcnt(3)
	v_mfma_f32_16x16x32_bf16 v[94:97], v[118:121], v[14:17], v[90:93]
	v_add_u32_e32 v21, 62, v194
	v_cmp_gt_u32_e64 s[16:17], s33, v20
	v_add_u32_e32 v20, 0x4e, v194
	v_mfma_f32_16x16x32_bf16 v[118:121], v[118:121], v[42:45], v[216:219]
	v_cmp_gt_u32_e64 s[14:15], s33, v21
	v_cmp_gt_u32_e64 s[26:27], s33, v18
	v_cmp_gt_u32_e64 s[30:31], s33, v20
	v_mfma_f32_16x16x32_bf16 v[106:109], v[98:101], v[14:17], v[90:93]
	v_add_u32_e32 v18, 46, v194
	v_add_u32_e32 v20, 49, v194
	v_add_u32_e32 v21, 48, v194
	s_waitcnt lgkmcnt(1)
	v_mfma_f32_16x16x32_bf16 v[90:93], v[208:211], v[14:17], v[90:93]
	v_cmp_gt_u32_e32 vcc, s33, v21
	v_cmp_gt_u32_e64 s[4:5], s33, v20
	v_cmp_gt_u32_e64 s[8:9], s33, v18
	v_mfma_f32_16x16x32_bf16 v[82:85], v[82:85], v[42:45], v[216:219]
	v_add_u32_e32 v18, 30, v194
	v_add_u32_e32 v20, 33, v194
	v_add_u32_e32 v21, 32, v194
	v_mfma_f32_16x16x32_bf16 v[98:101], v[98:101], v[42:45], v[216:219]
	v_cmp_gt_u32_e64 s[10:11], s33, v195
	v_cmp_gt_u32_e64 s[28:29], s33, v196
	v_cmp_gt_u32_e64 s[18:19], s33, v21
	v_mfma_f32_16x16x32_bf16 v[122:125], v[134:137], v[38:41], v[94:97]
	v_cmp_gt_u32_e64 s[20:21], s33, v20
	v_cmp_gt_u32_e64 s[22:23], s33, v18
	s_cmp_lg_u32 s53, 3
	v_mfma_f32_16x16x32_bf16 v[134:137], v[134:137], v[46:49], v[118:121]
	v_mfma_f32_16x16x32_bf16 v[118:121], v[208:211], v[42:45], v[216:219]
	v_mfma_f32_16x16x32_bf16 v[126:129], v[102:105], v[38:41], v[106:109]
	s_waitcnt lgkmcnt(0)
	v_mfma_f32_16x16x32_bf16 v[114:117], v[212:215], v[38:41], v[90:93]
	v_mfma_f32_16x16x32_bf16 v[142:145], v[86:89], v[46:49], v[82:85]
	ds_read_b64_tr_b16 v[94:95], v1 offset:8192
	s_nop 0
	ds_read_b64_tr_b16 v[90:91], v1 offset:8224
	ds_read_b64_tr_b16 v[86:87], v1 offset:8256
	ds_read_b64_tr_b16 v[82:83], v1 offset:8288
	ds_read_b64_tr_b16 v[96:97], v1 offset:10752
	ds_read_b64_tr_b16 v[92:93], v1 offset:10784
	ds_read_b64_tr_b16 v[88:89], v1 offset:10816
	ds_read_b64_tr_b16 v[84:85], v1 offset:10848
	v_mfma_f32_16x16x32_bf16 v[138:141], v[102:105], v[46:49], v[98:101]
	ds_read_b64_tr_b16 v[110:111], v1 offset:13312
	ds_read_b64_tr_b16 v[106:107], v1 offset:13344
	ds_read_b64_tr_b16 v[102:103], v1 offset:13376
	ds_read_b64_tr_b16 v[98:99], v1 offset:13408
	ds_read_b64_tr_b16 v[112:113], v1 offset:15872
	ds_read_b64_tr_b16 v[108:109], v1 offset:15904
	ds_read_b64_tr_b16 v[104:105], v1 offset:15936
	ds_read_b64_tr_b16 v[100:101], v1 offset:15968
	v_add_u32_e32 v1, 64, v194
	v_cmp_gt_u32_e64 s[6:7], s33, v1
	v_mfma_f32_16x16x32_bf16 v[118:121], v[212:215], v[46:49], v[118:121]
	v_add_u32_e32 v1, 0x4f, v194
	v_cmp_gt_u32_e64 s[34:35], s33, v1
	v_add_u32_e32 v1, 47, v194
	v_cmp_gt_u32_e64 s[12:13], s33, v1
	v_add_u32_e32 v1, 31, v194
	v_cmp_gt_u32_e64 s[24:25], s33, v1
	s_cselect_b32 s99, 1, 0
	s_bitcmp1_b32 s41, 8
	s_cbranch_scc1 .Lsw_h0_end
	s_waitcnt lgkmcnt(0)
	s_add_i32 s100, s53, -3
	s_cmp_ge_i32 s100, s45
	s_cbranch_scc1 .Lsw_h0_bar
	s_waitcnt vmcnt(3)
	ds_write_b128 v179, v[62:65] offset:18688
	s_waitcnt vmcnt(2)
	ds_write_b128 v191, v[66:69] offset:26880

; template <int TY> __device__ __forceinline__ void attn_unit(LAS unsigned char* lds, const AttnArgs& a, int b, int h, int qt, int wave_s) {
;     ...
;         if (J == 0) {
; #pragma unroll
;             for (int kb = 0; kb < 3; ++kb)
; #pragma unroll
;                 for (int qb = 0; qb < 2; ++qb) s[qb][kb] = (f32x4){-1e30f, -1e30f, -1e30f, -1e30f};
;         }
.Lsw_h0_end:
	s_cmp_lg_u32 s99, 0
	s_cbranch_scc1 .LBB0_801
	v_mov_b32_e32 v123, 0xf149f2ca
	v_mov_b32_e32 v125, 0xf149f2ca
	v_mov_b32_e32 v122, 0xf149f2ca
	v_mov_b32_e32 v124, 0xf149f2ca
	v_mov_b32_e32 v128, 0xf149f2ca
	v_mov_b32_e32 v129, 0xf149f2ca
	v_mov_b32_e32 v126, 0xf149f2ca
	v_mov_b32_e32 v127, 0xf149f2ca
	v_mov_b32_e32 v20, 0xf149f2ca
	v_mov_b32_e32 v21, 0xf149f2ca
	v_mov_b32_e32 v1, 0xf149f2ca
	v_mov_b32_e32 v18, 0xf149f2ca
	v_mov_b32_e32 v140, 0xf149f2ca
	v_mov_b32_e32 v141, 0xf149f2ca
	v_mov_b32_e32 v138, 0xf149f2ca
	v_mov_b32_e32 v139, 0xf149f2ca
	v_mov_b32_e32 v144, 0xf149f2ca
	v_mov_b32_e32 v145, 0xf149f2ca
	v_mov_b32_e32 v142, 0xf149f2ca
	v_mov_b32_e32 v143, 0xf149f2ca
	v_mov_b32_e32 v132, 0xf149f2ca
	v_mov_b32_e32 v133, 0xf149f2ca
	v_mov_b32_e32 v130, 0xf149f2ca
	v_mov_b32_e32 v131, 0xf149f2ca
	s_branch .LBB0_802

; __device__ __forceinline__ unsigned cvt_pk_bf16(float lo, float hi) { f32x2 v = {lo, hi}; bf16x2_t b = __builtin_convertvector(v, bf16x2_t); return __builtin_bit_cast(unsigned, b); }
; #define ATT_STORE(S, buf) do { LAS unsigned char* sb_ = lds + (buf) * BUFB; \
;         *(LAS u32x4*)(sb_ + kwoff) = kreg##S; \
;         if (TY == 2 && tid < 256) *(LAS u32x4*)(sb_ + kwoff2) = kreg2##S; \
;         *(LAS u32x4*)(sb_ + KBYTES + (ki * VSTR + kc * 8) * 2) = vreg##S; \
;         if (TY == 1 && tid < 64) *(LAS float*)(sb_ + KBYTES + VBYTES + tid * 4) = freg##S; } while (0)
; template <int TY> __device__ __forceinline__ void attn_unit(LAS unsigned char* lds, const AttnArgs& a, int b, int h, int qt, int wave_s) {
;     ...
; #pragma unroll
;         for (int qb = 0; qb < 2; ++qb) {
; #pragma unroll
;             for (int kb = 0; kb < 4; ++kb)
; #pragma unroll
;                 for (int r = 0; r < 4; ++r) s[qb][kb][r] = __builtin_amdgcn_exp2f(s[qb][kb][r]);
; #pragma unroll
;             for (int G = 0; G < 2; ++G) {
;                 u32x4 w; w.x = cvt_pk_bf16(s[qb][2 * G][0], s[qb][2 * G][1]); w.y = cvt_pk_bf16(s[qb][2 * G][2], s[qb][2 * G][3]);
;                 w.z = cvt_pk_bf16(s[qb][2 * G + 1][0], s[qb][2 * G + 1][1]); w.w = cvt_pk_bf16(s[qb][2 * G + 1][2], s[qb][2 * G + 1][3]);
;                 pf[qb][G] = __builtin_bit_cast(bf16x8, w);
;             }
;         }
; #pragma unroll
;         for (int G = 0; G < 2; ++G) {
;             lacc[0] = __builtin_amdgcn_mfma_f32_16x16x32_bf16(ones, pf[0][G], lacc[0], 0, 0, 0);
;             lacc[1] = __builtin_amdgcn_mfma_f32_16x16x32_bf16(ones, pf[1][G], lacc[1], 0, 0, 0);
;         }
; #pragma unroll
;         for (int db = 0; db < 4; ++db)
; #pragma unroll
;             for (int G = 0; G < 2; ++G) {
;                 o[0][db] = __builtin_amdgcn_mfma_f32_16x16x32_bf16(vf[db][G], pf[0][G], o[0][db], 0, 0, 0);
;                 o[1][db] = __builtin_amdgcn_mfma_f32_16x16x32_bf16(vf[db][G], pf[1][G], o[1][db], 0, 0, 0);
;             }
;         }
;         if (J < J1) { if (hf == 0) ATT_STORE(B, 1); else ATT_STORE(A, 0); }
;         __syncthreads();
.LBB0_804:
	v_exp_f32_e32 v120, v132
	v_exp_f32_e32 v121, v133
	v_exp_f32_e32 v130, v130
	v_exp_f32_e32 v131, v131
	v_exp_f32_e32 v132, v144
	v_exp_f32_e32 v133, v145
	v_exp_f32_e32 v136, v142
	v_exp_f32_e32 v137, v143
	v_cvt_pk_bf16_f32 v120, v120, v121
	v_exp_f32_e32 v20, v20
	v_exp_f32_e32 v21, v21
	v_exp_f32_e32 v1, v1
	v_exp_f32_e32 v18, v18
	v_exp_f32_e32 v121, v128
	v_exp_f32_e32 v128, v129
	v_exp_f32_e32 v126, v126
	v_exp_f32_e32 v127, v127
	v_exp_f32_e32 v123, v123
	v_exp_f32_e32 v125, v125
	v_exp_f32_e32 v122, v122
	v_exp_f32_e32 v129, v124
	v_exp_f32_e32 v140, v140
	v_exp_f32_e32 v141, v141
	v_exp_f32_e32 v138, v138
	v_exp_f32_e32 v139, v139
	v_exp_f32_e32 v135, v135
	v_exp_f32_e32 v134, v134
	v_exp_f32_e32 v142, v119
	v_exp_f32_e32 v143, v118
	v_exp_f32_e32 v144, v117
	v_exp_f32_e32 v145, v116
	v_cvt_pk_bf16_f32 v116, v20, v21
	v_cvt_pk_bf16_f32 v117, v1, v18
	v_cvt_pk_bf16_f32 v118, v121, v128
	v_cvt_pk_bf16_f32 v119, v126, v127
	v_cvt_pk_bf16_f32 v124, v123, v125
	v_cvt_pk_bf16_f32 v125, v122, v129
	v_cvt_pk_bf16_f32 v121, v130, v131
	v_cvt_pk_bf16_f32 v122, v132, v133
	v_cvt_pk_bf16_f32 v123, v136, v137
	v_exp_f32_e32 v1, v115
	v_exp_f32_e32 v18, v114
	v_mfma_f32_16x16x32_bf16 v[6:9], v[54:57], v[116:119], v[6:9]
	v_cvt_pk_bf16_f32 v126, v142, v143
	v_cvt_pk_bf16_f32 v127, v144, v145
	v_cvt_pk_bf16_f32 v128, v140, v141
	s_waitcnt lgkmcnt(11)
	v_mfma_f32_16x16x32_bf16 v[70:73], v[94:97], v[120:123], v[70:73]
	v_cvt_pk_bf16_f32 v129, v138, v139
	v_cvt_pk_bf16_f32 v130, v135, v134
	v_cvt_pk_bf16_f32 v131, v1, v18
	v_mfma_f32_16x16x32_bf16 v[34:37], v[94:97], v[116:119], v[34:37]
	s_waitcnt lgkmcnt(10)
	v_mfma_f32_16x16x32_bf16 v[58:61], v[90:93], v[120:123], v[58:61]
	v_mfma_f32_16x16x32_bf16 v[30:33], v[90:93], v[116:119], v[30:33]
	s_waitcnt lgkmcnt(9)
	v_mfma_f32_16x16x32_bf16 v[50:53], v[86:89], v[120:123], v[50:53]
	v_mfma_f32_16x16x32_bf16 v[26:29], v[86:89], v[116:119], v[26:29]
	s_waitcnt lgkmcnt(8)
	v_mfma_f32_16x16x32_bf16 v[10:13], v[82:85], v[120:123], v[10:13]
	v_mfma_f32_16x16x32_bf16 v[20:23], v[82:85], v[116:119], v[22:25]
	v_mfma_f32_16x16x32_bf16 v[2:5], v[54:57], v[120:123], v[2:5]
	v_mfma_f32_16x16x32_bf16 v[6:9], v[54:57], v[124:127], v[6:9]
	s_waitcnt lgkmcnt(3)
	v_mfma_f32_16x16x32_bf16 v[70:73], v[110:113], v[128:131], v[70:73]
	v_mfma_f32_16x16x32_bf16 v[34:37], v[110:113], v[124:127], v[34:37]
	s_waitcnt lgkmcnt(2)
	v_mfma_f32_16x16x32_bf16 v[58:61], v[106:109], v[128:131], v[58:61]
	v_mfma_f32_16x16x32_bf16 v[30:33], v[106:109], v[124:127], v[30:33]
	s_waitcnt lgkmcnt(1)
	v_mfma_f32_16x16x32_bf16 v[50:53], v[102:105], v[128:131], v[50:53]
	v_mfma_f32_16x16x32_bf16 v[26:29], v[102:105], v[124:127], v[26:29]
	s_waitcnt lgkmcnt(0)
	v_mfma_f32_16x16x32_bf16 v[10:13], v[98:101], v[128:131], v[10:13]
	v_mfma_f32_16x16x32_bf16 v[22:25], v[98:101], v[124:127], v[20:23]
	v_mfma_f32_16x16x32_bf16 v[2:5], v[54:57], v[128:131], v[2:5]
	s_bitcmp1_b32 s41, 8
	s_cbranch_scc1 .LBB0_805
	s_add_i32 s6, s53, -3
	s_cmp_lt_i32 s6, s45
	s_cselect_b64 s[4:5], -1, 0
	s_andn2_b64 vcc, exec, s[4:5]
	s_cbranch_vccnz .LBB0_797
	s_branch .Lsw_h0_cont

; #define LAS __attribute__((address_space(3)))
; #define ATT_STORE(S, buf) do { LAS unsigned char* sb_ = lds + (buf) * BUFB; \
;         *(LAS u32x4*)(sb_ + kwoff) = kreg##S; \
;         if (TY == 2 && tid < 256) *(LAS u32x4*)(sb_ + kwoff2) = kreg2##S; \
;         *(LAS u32x4*)(sb_ + KBYTES + (ki * VSTR + kc * 8) * 2) = vreg##S; \
;         if (TY == 1 && tid < 64) *(LAS float*)(sb_ + KBYTES + VBYTES + tid * 4) = freg##S; } while (0)
; template <int TY> __device__ __forceinline__ void attn_unit(LAS unsigned char* lds, const AttnArgs& a, int b, int h, int qt, int wave_s) {
;     ...
;         { const int Jn = J + 2 <= J1 ? J + 2 : J1; if (hf == 0) ATT_LOAD(A, Jn); else ATT_LOAD(B, Jn); }
;         const bool skip = (64 * J > ewhi) || (TY == 0 && 64 * J + 63 + 127 < ewlo);
;         if (!skip) {
;         int lim[2]; f32x4 cinit[2];
; #pragma unroll
;         for (int qb = 0; qb < 2; ++qb) {
;             lim[qb] = eq[qb] - 64 * J - 4 * fq;
;             const float c0 = TY == 0 ? -(mrun[qb] + slope2 * (float)lim[qb]) : -mrun[qb];
;             cinit[qb] = (f32x4){c0, c0, c0, c0};
;         }
;         f32x4 s[2][4];
;         bf16x8 kfr[4][NDS];
; #pragma unroll
;         for (int kb = 0; kb < 4; ++kb)
; #pragma unroll
;             for (int ds = 0; ds < NDS; ++ds) kfr[kb][ds] = *(const LAS bf16x8*)(sb + koff + (kb * NDS + ds) * 1024);
; #pragma unroll
;         for (int kb = 0; kb < 4; ++kb) {
; #pragma unroll
;             for (int ds = 0; ds < NDS; ++ds) {
;                 s[0][kb] = __builtin_amdgcn_mfma_f32_16x16x32_bf16(kfr[kb][ds], qf[0][ds], ds == 0 ? cinit[0] : s[0][kb], 0, 0, 0);
;                 s[1][kb] = __builtin_amdgcn_mfma_f32_16x16x32_bf16(kfr[kb][ds], qf[1][ds], ds == 0 ? cinit[1] : s[1][kb], 0, 0, 0);
;             }
;         }
;         bf16x8 vf[4][2];
; #pragma unroll
;         for (int db = 0; db < 4; ++db)
; #pragma unroll
;             for (int G = 0; G < 2; ++G) {
;                 LAS unsigned char* vp = sb + voff + (32 * G * VSTR + 16 * db) * 2;
;                 const v4i16_t lo = __builtin_amdgcn_ds_read_tr16_b64_v4i16((LAS v4i16_t*)vp), hi = __builtin_amdgcn_ds_read_tr16_b64_v4i16((LAS v4i16_t*)(vp + 16 * VSTR * 2));
;                 vf[db][G] = (bf16x8){lo[0], lo[1], lo[2], lo[3], hi[0], hi[1], hi[2], hi[3]};
;             }
;     ...
;         if (J < J1) { if (hf == 0) ATT_STORE(B, 1); else ATT_STORE(A, 0); }
;         __syncthreads();
.Lsw_h0_cont:
	s_min_i32 s4, s53, s45
	v_lshl_add_u32 v1, s4, 6, v155
	v_max_i32_e32 v20, 48, v1
	v_add_u32_e32 v18, s42, v1
	v_add_u32_e32 v20, s47, v20
	v_cmp_lt_i32_e32 vcc, 63, v1
	s_nop 1
	v_cndmask_b32_e32 v1, v20, v18, vcc
	v_mad_i64_i32 v[20:21], s[4:5], v1, s40, v[160:161]
	s_waitcnt vmcnt(2)
	v_mad_i64_i32 v[66:67], s[4:5], v1, s40, v[162:163]
	global_load_dwordx4 v[62:65], v[20:21], off
	s_nop 0
	global_load_dwordx4 v[66:69], v[66:67], off
	s_add_i32 s4, s48, 64
	s_cmp_gt_i32 s4, s46
	s_cselect_b64 s[4:5], -1, 0
	s_add_i32 s6, s48, 0xfe
	s_cmp_lt_i32 s6, s52
	s_cselect_b64 s[6:7], -1, 0
	s_or_b64 s[4:5], s[4:5], s[6:7]
	s_and_b64 vcc, exec, s[4:5]
	s_cbranch_vccnz .LBB0_815
	v_add_u32_e32 v195, 1, v194
	v_cvt_f32_i32_e32 v18, v195
	v_add_u32_e32 v1, 0, v193
	ds_read_b128 v[82:85], v1 offset:18688
	ds_read_b128 v[86:89], v1 offset:19712
	ds_read_b128 v[98:101], v1 offset:20736
	ds_read_b128 v[102:105], v1 offset:21760
	ds_read_b128 v[118:121], v1 offset:22784
	ds_read_b128 v[138:141], v1 offset:23808
	v_add_u32_e32 v196, 17, v194
	v_fma_f32 v18, v157, v18, v159
	ds_read_b128 v[208:211], v1 offset:24832
	ds_read_b128 v[212:215], v1 offset:25856
	v_cvt_f32_i32_e32 v1, v196
	v_xor_b32_e32 v90, 0x80000000, v18
	v_mov_b32_e32 v91, v90
	v_mov_b32_e32 v92, v90
	v_mov_b32_e32 v93, v90
	v_fma_f32 v1, v157, v1, v158
	v_xor_b32_e32 v216, 0x80000000, v1
	s_waitcnt lgkmcnt(7)
	v_mfma_f32_16x16x32_bf16 v[94:97], v[82:85], v[14:17], v[90:93]
	v_mov_b32_e32 v217, v216
	v_mov_b32_e32 v218, v216
	v_mov_b32_e32 v219, v216
	s_waitcnt lgkmcnt(6)
	v_mfma_f32_16x16x32_bf16 v[130:133], v[86:89], v[38:41], v[94:97]
	v_add_u32_e32 v1, 0, v192
	v_add_u32_e32 v18, -1, v194
	v_add_u32_e32 v20, -2, v194
	s_waitcnt lgkmcnt(3)
	v_mfma_f32_16x16x32_bf16 v[94:97], v[118:121], v[14:17], v[90:93]
	v_cmp_gt_u32_e64 s[14:15], s33, v20
	v_cmp_gt_u32_e64 s[16:17], s33, v18
	v_add_u32_e32 v18, 15, v194
	v_mfma_f32_16x16x32_bf16 v[118:121], v[118:121], v[42:45], v[216:219]
	v_add_u32_e32 v20, 14, v194
	v_cmp_gt_u32_e64 s[30:31], s33, v20
	v_cmp_gt_u32_e64 s[34:35], s33, v18
	v_mfma_f32_16x16x32_bf16 v[106:109], v[98:101], v[14:17], v[90:93]
	v_add_u32_e32 v18, -15, v194
	v_add_u32_e32 v20, -16, v194
	v_subrev_u32_e32 v21, 18, v194
	s_waitcnt lgkmcnt(1)
	v_mfma_f32_16x16x32_bf16 v[90:93], v[208:211], v[14:17], v[90:93]
	v_cmp_gt_u32_e32 vcc, s33, v20
	v_cmp_gt_u32_e64 s[6:7], s33, v18
	v_cmp_gt_u32_e64 s[8:9], s33, v21
	v_mfma_f32_16x16x32_bf16 v[82:85], v[82:85], v[42:45], v[216:219]
	v_subrev_u32_e32 v18, 34, v194
	v_subrev_u32_e32 v20, 31, v194
	v_subrev_u32_e32 v21, 32, v194
	v_mfma_f32_16x16x32_bf16 v[98:101], v[98:101], v[42:45], v[216:219]
	v_cmp_gt_u32_e64 s[4:5], s33, v194
	v_cmp_gt_u32_e64 s[10:11], s33, v195
	v_cmp_gt_u32_e64 s[28:29], s33, v196
	v_mfma_f32_16x16x32_bf16 v[122:125], v[138:141], v[38:41], v[94:97]
	v_cmp_gt_u32_e64 s[18:19], s33, v21
	v_cmp_gt_u32_e64 s[20:21], s33, v20
	v_cmp_gt_u32_e64 s[22:23], s33, v18
	v_mfma_f32_16x16x32_bf16 v[138:141], v[138:141], v[46:49], v[118:121]
	s_cmp_lg_u32 s53, 2
	v_mfma_f32_16x16x32_bf16 v[118:121], v[208:211], v[42:45], v[216:219]
	v_mfma_f32_16x16x32_bf16 v[126:129], v[102:105], v[38:41], v[106:109]
	s_waitcnt lgkmcnt(0)
	v_mfma_f32_16x16x32_bf16 v[114:117], v[212:215], v[38:41], v[90:93]
	v_mfma_f32_16x16x32_bf16 v[142:145], v[86:89], v[46:49], v[82:85]
	ds_read_b64_tr_b16 v[94:95], v1 offset:26880
	s_nop 0
	ds_read_b64_tr_b16 v[90:91], v1 offset:26912
	ds_read_b64_tr_b16 v[86:87], v1 offset:26944
	ds_read_b64_tr_b16 v[82:83], v1 offset:26976
	ds_read_b64_tr_b16 v[96:97], v1 offset:29440
	ds_read_b64_tr_b16 v[92:93], v1 offset:29472
	ds_read_b64_tr_b16 v[88:89], v1 offset:29504
	ds_read_b64_tr_b16 v[84:85], v1 offset:29536
	v_mfma_f32_16x16x32_bf16 v[134:137], v[102:105], v[46:49], v[98:101]
	ds_read_b64_tr_b16 v[110:111], v1 offset:32000
	ds_read_b64_tr_b16 v[106:107], v1 offset:32032
	ds_read_b64_tr_b16 v[102:103], v1 offset:32064
	ds_read_b64_tr_b16 v[98:99], v1 offset:32096
	ds_read_b64_tr_b16 v[112:113], v1 offset:34560
	ds_read_b64_tr_b16 v[108:109], v1 offset:34592
	ds_read_b64_tr_b16 v[104:105], v1 offset:34624
	ds_read_b64_tr_b16 v[100:101], v1 offset:34656
	v_add_u32_e32 v1, 16, v194
	v_mfma_f32_16x16x32_bf16 v[118:121], v[212:215], v[46:49], v[118:121]
	v_cmp_gt_u32_e64 s[26:27], s33, v1
	v_subrev_u32_e32 v1, 17, v194
	v_cmp_gt_u32_e64 s[12:13], s33, v1
	v_subrev_u32_e32 v1, 33, v194
	v_cmp_gt_u32_e64 s[24:25], s33, v1
	s_cselect_b32 s99, 1, 0
	s_bitcmp1_b32 s41, 8
	s_cbranch_scc1 .Lsw_h1_end
	s_waitcnt lgkmcnt(0)
	s_add_i32 s100, s53, -2
	s_cmp_ge_i32 s100, s45
	s_cbranch_scc1 .Lsw_h1_bar
	s_waitcnt vmcnt(3)
	ds_write_b128 v179, v[74:77]
	s_waitcnt vmcnt(2)
	ds_write_b128 v191, v[78:81] offset:8192

; template <int TY> __device__ __forceinline__ void attn_unit(LAS unsigned char* lds, const AttnArgs& a, int b, int h, int qt, int wave_s) {
;     ...
;         if (J == 0) {
; #pragma unroll
;             for (int kb = 0; kb < 3; ++kb)
; #pragma unroll
;                 for (int qb = 0; qb < 2; ++qb) s[qb][kb] = (f32x4){-1e30f, -1e30f, -1e30f, -1e30f};
;         }
.Lsw_h1_end:
	s_cmp_lg_u32 s99, 0
	s_cbranch_scc1 .LBB0_811
	v_mov_b32_e32 v123, 0xf149f2ca
	v_mov_b32_e32 v125, 0xf149f2ca
	v_mov_b32_e32 v122, 0xf149f2ca
	v_mov_b32_e32 v124, 0xf149f2ca
	v_mov_b32_e32 v128, 0xf149f2ca
	v_mov_b32_e32 v129, 0xf149f2ca
	v_mov_b32_e32 v126, 0xf149f2ca
	v_mov_b32_e32 v127, 0xf149f2ca
	v_mov_b32_e32 v20, 0xf149f2ca
	v_mov_b32_e32 v21, 0xf149f2ca
	v_mov_b32_e32 v1, 0xf149f2ca
	v_mov_b32_e32 v18, 0xf149f2ca
	v_mov_b32_e32 v136, 0xf149f2ca
	v_mov_b32_e32 v137, 0xf149f2ca
	v_mov_b32_e32 v134, 0xf149f2ca
	v_mov_b32_e32 v135, 0xf149f2ca
	v_mov_b32_e32 v144, 0xf149f2ca
	v_mov_b32_e32 v145, 0xf149f2ca
	v_mov_b32_e32 v142, 0xf149f2ca
	v_mov_b32_e32 v143, 0xf149f2ca
	v_mov_b32_e32 v132, 0xf149f2ca
	v_mov_b32_e32 v133, 0xf149f2ca
	v_mov_b32_e32 v130, 0xf149f2ca
	v_mov_b32_e32 v131, 0xf149f2ca
	s_branch .LBB0_812

; __device__ __forceinline__ unsigned cvt_pk_bf16(float lo, float hi) { f32x2 v = {lo, hi}; bf16x2_t b = __builtin_convertvector(v, bf16x2_t); return __builtin_bit_cast(unsigned, b); }
; #define ATT_STORE(S, buf) do { LAS unsigned char* sb_ = lds + (buf) * BUFB; \
;         *(LAS u32x4*)(sb_ + kwoff) = kreg##S; \
;         if (TY == 2 && tid < 256) *(LAS u32x4*)(sb_ + kwoff2) = kreg2##S; \
;         *(LAS u32x4*)(sb_ + KBYTES + (ki * VSTR + kc * 8) * 2) = vreg##S; \
;         if (TY == 1 && tid < 64) *(LAS float*)(sb_ + KBYTES + VBYTES + tid * 4) = freg##S; } while (0)
; template <int TY> __device__ __forceinline__ void attn_unit(LAS unsigned char* lds, const AttnArgs& a, int b, int h, int qt, int wave_s) {
;     ...
; #pragma unroll
;         for (int qb = 0; qb < 2; ++qb) {
; #pragma unroll
;             for (int kb = 0; kb < 4; ++kb)
; #pragma unroll
;                 for (int r = 0; r < 4; ++r) s[qb][kb][r] = __builtin_amdgcn_exp2f(s[qb][kb][r]);
; #pragma unroll
;             for (int G = 0; G < 2; ++G) {
;                 u32x4 w; w.x = cvt_pk_bf16(s[qb][2 * G][0], s[qb][2 * G][1]); w.y = cvt_pk_bf16(s[qb][2 * G][2], s[qb][2 * G][3]);
;                 w.z = cvt_pk_bf16(s[qb][2 * G + 1][0], s[qb][2 * G + 1][1]); w.w = cvt_pk_bf16(s[qb][2 * G + 1][2], s[qb][2 * G + 1][3]);
;                 pf[qb][G] = __builtin_bit_cast(bf16x8, w);
;             }
;         }
; #pragma unroll
;         for (int G = 0; G < 2; ++G) {
;             lacc[0] = __builtin_amdgcn_mfma_f32_16x16x32_bf16(ones, pf[0][G], lacc[0], 0, 0, 0);
;             lacc[1] = __builtin_amdgcn_mfma_f32_16x16x32_bf16(ones, pf[1][G], lacc[1], 0, 0, 0);
;         }
; #pragma unroll
;         for (int db = 0; db < 4; ++db)
; #pragma unroll
;             for (int G = 0; G < 2; ++G) {
;                 o[0][db] = __builtin_amdgcn_mfma_f32_16x16x32_bf16(vf[db][G], pf[0][G], o[0][db], 0, 0, 0);
;                 o[1][db] = __builtin_amdgcn_mfma_f32_16x16x32_bf16(vf[db][G], pf[1][G], o[1][db], 0, 0, 0);
;             }
;         }
;         if (J < J1) { if (hf == 0) ATT_STORE(B, 1); else ATT_STORE(A, 0); }
;         __syncthreads();
.LBB0_814:
	v_exp_f32_e32 v120, v132
	v_exp_f32_e32 v121, v133
	v_exp_f32_e32 v130, v130
	v_exp_f32_e32 v131, v131
	v_exp_f32_e32 v132, v144
	v_exp_f32_e32 v133, v145
	v_exp_f32_e32 v140, v142
	v_exp_f32_e32 v141, v143
	v_cvt_pk_bf16_f32 v120, v120, v121
	v_exp_f32_e32 v20, v20
	v_exp_f32_e32 v21, v21
	v_exp_f32_e32 v1, v1
	v_exp_f32_e32 v18, v18
	v_exp_f32_e32 v121, v128
	v_exp_f32_e32 v128, v129
	v_exp_f32_e32 v126, v126
	v_exp_f32_e32 v127, v127
	v_exp_f32_e32 v123, v123
	v_exp_f32_e32 v125, v125
	v_exp_f32_e32 v122, v122
	v_exp_f32_e32 v129, v124
	v_exp_f32_e32 v136, v136
	v_exp_f32_e32 v137, v137
	v_exp_f32_e32 v134, v134
	v_exp_f32_e32 v135, v135
	v_exp_f32_e32 v139, v139
	v_exp_f32_e32 v138, v138
	v_exp_f32_e32 v142, v119
	v_exp_f32_e32 v143, v118
	v_exp_f32_e32 v144, v117
	v_exp_f32_e32 v145, v116
	v_cvt_pk_bf16_f32 v116, v20, v21
	v_cvt_pk_bf16_f32 v117, v1, v18
	v_cvt_pk_bf16_f32 v118, v121, v128
	v_cvt_pk_bf16_f32 v119, v126, v127
	v_cvt_pk_bf16_f32 v124, v123, v125
	v_cvt_pk_bf16_f32 v125, v122, v129
	v_cvt_pk_bf16_f32 v121, v130, v131
	v_cvt_pk_bf16_f32 v122, v132, v133
	v_cvt_pk_bf16_f32 v123, v140, v141
	v_exp_f32_e32 v1, v115
	v_exp_f32_e32 v18, v114
	v_mfma_f32_16x16x32_bf16 v[6:9], v[54:57], v[116:119], v[6:9]
	v_cvt_pk_bf16_f32 v126, v142, v143
	v_cvt_pk_bf16_f32 v127, v144, v145
	v_cvt_pk_bf16_f32 v128, v136, v137
	s_waitcnt lgkmcnt(11)
	v_mfma_f32_16x16x32_bf16 v[70:73], v[94:97], v[120:123], v[70:73]
	v_cvt_pk_bf16_f32 v129, v134, v135
	v_cvt_pk_bf16_f32 v130, v139, v138
	v_cvt_pk_bf16_f32 v131, v1, v18
	v_mfma_f32_16x16x32_bf16 v[34:37], v[94:97], v[116:119], v[34:37]
	s_waitcnt lgkmcnt(10)
	v_mfma_f32_16x16x32_bf16 v[58:61], v[90:93], v[120:123], v[58:61]
	v_mfma_f32_16x16x32_bf16 v[30:33], v[90:93], v[116:119], v[30:33]
	s_waitcnt lgkmcnt(9)
	v_mfma_f32_16x16x32_bf16 v[50:53], v[86:89], v[120:123], v[50:53]
	v_mfma_f32_16x16x32_bf16 v[26:29], v[86:89], v[116:119], v[26:29]
	s_waitcnt lgkmcnt(8)
	v_mfma_f32_16x16x32_bf16 v[10:13], v[82:85], v[120:123], v[10:13]
	v_mfma_f32_16x16x32_bf16 v[20:23], v[82:85], v[116:119], v[22:25]
	v_mfma_f32_16x16x32_bf16 v[2:5], v[54:57], v[120:123], v[2:5]
	v_mfma_f32_16x16x32_bf16 v[6:9], v[54:57], v[124:127], v[6:9]
	s_waitcnt lgkmcnt(3)
	v_mfma_f32_16x16x32_bf16 v[70:73], v[110:113], v[128:131], v[70:73]
	v_mfma_f32_16x16x32_bf16 v[34:37], v[110:113], v[124:127], v[34:37]
	s_waitcnt lgkmcnt(2)
	v_mfma_f32_16x16x32_bf16 v[58:61], v[106:109], v[128:131], v[58:61]
	v_mfma_f32_16x16x32_bf16 v[30:33], v[106:109], v[124:127], v[30:33]
	s_waitcnt lgkmcnt(1)
	v_mfma_f32_16x16x32_bf16 v[50:53], v[102:105], v[128:131], v[50:53]
	v_mfma_f32_16x16x32_bf16 v[26:29], v[102:105], v[124:127], v[26:29]
	s_waitcnt lgkmcnt(0)
	v_mfma_f32_16x16x32_bf16 v[10:13], v[98:101], v[128:131], v[10:13]
	v_mfma_f32_16x16x32_bf16 v[22:25], v[98:101], v[124:127], v[20:23]
	v_mfma_f32_16x16x32_bf16 v[2:5], v[54:57], v[128:131], v[2:5]
	s_bitcmp1_b32 s41, 8
	s_cbranch_scc0 .LBB0_797
